# NA bias table with 32-float rows and a -1e30 sentinel column: out-of-window elements index the sentinel, no pre-init/select per element
# baseline (speedup 1.0000x reference)
.Lna_map_done:
	v_readlane_b32 s40, v254, 0
	v_readlane_b32 s50, v254, 10
	v_readlane_b32 s51, v254, 11
	s_add_u32 s2, s50, s0
	s_addc_u32 s3, s51, s1
	v_readlane_b32 s0, v254, 39
	v_readlane_b32 s1, v254, 40
	s_mulk_i32 s0, 0x744
	s_ashr_i32 s1, s0, 31
	s_lshl_b64 s[0:1], s[0:1], 2
	s_add_u32 s2, s2, s0
	s_addc_u32 s3, s3, s1
	s_ashr_i32 s0, s22, 6
	s_and_b32 s26, s0, 3
	v_and_b32_e32 v3, 15, v1
	s_mulk_i32 s0, 0x4c00
	v_sub_u32_e64 v0, s26, 1 clamp
	v_lshl_or_b32 v205, s26, 4, v3
	s_add_i32 s40, s0, 0
	v_cmp_gt_u32_e64 s[0:1], 2, v0
	v_bfe_u32 v2, v1, 4, 2
	v_sub_u32_e64 v0, v205, 8 clamp
	v_min_u32_e32 v4, 48, v0
	v_lshlrev_b32_e32 v0, 2, v2
	v_or_b32_e32 v7, 1, v0
	v_sub_u32_e32 v8, v7, v205
	v_readlane_b32 s41, v254, 1
	v_readlane_b32 s42, v254, 2
	v_readlane_b32 s43, v254, 3
	v_readlane_b32 s44, v254, 4
	v_readlane_b32 s45, v254, 5
	v_readlane_b32 s46, v254, 6
	v_readlane_b32 s47, v254, 7
	v_readlane_b32 s48, v254, 8
	v_readlane_b32 s49, v254, 9
	v_readlane_b32 s52, v254, 12
	v_readlane_b32 s53, v254, 13
	v_readlane_b32 s54, v254, 14
	v_readlane_b32 s55, v254, 15
	v_writelane_b32 v254, s0, 27
	v_max_i32_e32 v8, -15, v8
	v_add_u32_e32 v8, 15, v8
	v_writelane_b32 v254, s1, 28
	v_cmp_ge_u32_e64 s[0:1], v7, v4
	v_sub_u32_e32 v6, v0, v205
	v_max_i32_e32 v6, -15, v6
	v_cndmask_b32_e64 v7, -1, v8, s[0:1]
	v_or_b32_e32 v8, 2, v0
	v_sub_u32_e32 v9, v8, v205
	v_max_i32_e32 v9, -15, v9
	v_add_u32_e32 v9, 15, v9
	v_cmp_ge_u32_e64 s[0:1], v8, v4
	v_add_u32_e32 v6, 15, v6
	v_cmp_lt_u32_e32 vcc, v0, v4
	v_cndmask_b32_e64 v8, -1, v9, s[0:1]
	v_or_b32_e32 v9, 3, v0
	v_sub_u32_e32 v10, v9, v205
	v_max_i32_e32 v10, -15, v10
	v_add_u32_e32 v10, 15, v10
	v_cmp_ge_u32_e64 s[0:1], v9, v4
	v_add_u32_e32 v5, 16, v4
	v_cndmask_b32_e64 v6, v6, -1, vcc
	v_cndmask_b32_e64 v9, -1, v10, s[0:1]
	v_or_b32_e32 v10, 16, v0
	v_cmp_ge_u32_e64 s[0:1], v10, v4
	v_sub_u32_e32 v10, v10, v205
	v_med3_i32 v10, v10, -15, 15
	v_add_u32_e32 v10, 15, v10
	s_and_b64 vcc, s[0:1], vcc
	v_or_b32_e32 v11, 17, v0
	v_cndmask_b32_e32 v10, -1, v10, vcc
	v_cmp_ge_u32_e32 vcc, v11, v4
	v_cmp_lt_u32_e64 s[0:1], v11, v5
	v_sub_u32_e32 v11, v11, v205
	v_med3_i32 v11, v11, -15, 15
	v_add_u32_e32 v11, 15, v11
	s_and_b64 vcc, vcc, s[0:1]
	v_or_b32_e32 v12, 18, v0
	v_cndmask_b32_e32 v11, -1, v11, vcc
	v_cmp_ge_u32_e32 vcc, v12, v4
	v_cmp_lt_u32_e64 s[0:1], v12, v5
	v_sub_u32_e32 v12, v12, v205
	v_med3_i32 v12, v12, -15, 15
	v_add_u32_e32 v12, 15, v12
	s_and_b64 vcc, vcc, s[0:1]
	v_or_b32_e32 v13, 19, v0
	v_cndmask_b32_e32 v12, -1, v12, vcc
	v_cmp_ge_u32_e32 vcc, v13, v4
	v_cmp_lt_u32_e64 s[0:1], v13, v5
	v_sub_u32_e32 v13, v13, v205
	v_med3_i32 v13, v13, -15, 15
	v_add_u32_e32 v13, 15, v13
	s_and_b64 vcc, vcc, s[0:1]
	v_or_b32_e32 v14, 32, v0
	v_cndmask_b32_e32 v13, -1, v13, vcc
	v_cmp_ge_u32_e32 vcc, v14, v4
	v_cmp_lt_u32_e64 s[0:1], v14, v5
	v_sub_u32_e32 v14, v14, v205
	v_med3_i32 v14, v14, -15, 15
	v_add_u32_e32 v14, 15, v14
	s_and_b64 vcc, vcc, s[0:1]
	v_or_b32_e32 v15, 33, v0
	v_cndmask_b32_e32 v14, -1, v14, vcc
	v_cmp_ge_u32_e32 vcc, v15, v4
	v_cmp_lt_u32_e64 s[0:1], v15, v5
	v_sub_u32_e32 v15, v15, v205
	v_med3_i32 v15, v15, -15, 15
	v_add_u32_e32 v15, 15, v15
	s_and_b64 vcc, vcc, s[0:1]
	v_or_b32_e32 v16, 34, v0
	v_cndmask_b32_e32 v15, -1, v15, vcc
	v_cmp_ge_u32_e32 vcc, v16, v4
	v_cmp_lt_u32_e64 s[0:1], v16, v5
	v_sub_u32_e32 v16, v16, v205
	v_med3_i32 v16, v16, -15, 15
	v_add_u32_e32 v16, 15, v16
	s_and_b64 vcc, vcc, s[0:1]
	v_or_b32_e32 v17, 35, v0
	v_cndmask_b32_e32 v16, -1, v16, vcc
	v_cmp_ge_u32_e32 vcc, v17, v4
	v_cmp_lt_u32_e64 s[0:1], v17, v5
	v_sub_u32_e32 v4, v17, v205
	v_or_b32_e32 v17, 48, v0
	v_med3_i32 v4, v4, -15, 15
	v_sub_u32_e32 v18, v17, v205
	v_add_u32_e32 v4, 15, v4
	s_and_b64 vcc, vcc, s[0:1]
	v_min_i32_e32 v18, 15, v18
	v_cndmask_b32_e32 v4, -1, v4, vcc
	v_add_u32_e32 v18, 15, v18
	v_cmp_lt_u32_e32 vcc, v17, v5
	v_and_b32_e32 v179, 63, v1
	v_or_b32_e32 v22, 0x1c0, v179
	v_cndmask_b32_e32 v17, -1, v18, vcc
	v_or_b32_e32 v18, 49, v0
	v_sub_u32_e32 v19, v18, v205
	v_min_i32_e32 v19, 15, v19
	v_add_u32_e32 v19, 15, v19
	v_cmp_lt_u32_e32 vcc, v18, v5
	v_lshrrev_b32_e32 v23, 3, v22
	v_mul_u32_u24_e32 v24, 0x910, v23
	v_cndmask_b32_e32 v18, -1, v19, vcc
	v_or_b32_e32 v19, 50, v0
	v_sub_u32_e32 v20, v19, v205
	v_min_i32_e32 v20, 15, v20
	v_add_u32_e32 v20, 15, v20
	v_cmp_lt_u32_e32 vcc, v19, v5
	s_add_i32 s23, s26, 1
	s_cmp_lg_u32 s26, 3
	v_cndmask_b32_e32 v19, -1, v20, vcc
	v_or_b32_e32 v20, 51, v0
	v_sub_u32_e32 v21, v20, v205
	v_min_i32_e32 v21, 15, v21
	v_cmp_lt_u32_e32 vcc, v20, v5
	v_lshlrev_b32_e32 v20, 3, v1
	v_add_u32_e32 v21, 15, v21
	v_and_b32_e32 v20, 56, v20
	v_cndmask_b32_e32 v5, -1, v21, vcc
	v_or_b32_e32 v21, 0x200, v20
	v_add_lshl_u32 v108, v24, v21, 1
	v_or_b32_e32 v24, 0x180, v179
	v_lshrrev_b32_e32 v24, 3, v24
	v_mul_u32_u24_e32 v25, 0x910, v24
	v_add_lshl_u32 v110, v25, v21, 1
	v_or_b32_e32 v25, 0x140, v179
	v_lshrrev_b32_e32 v25, 3, v25
	v_mul_u32_u24_e32 v26, 0x910, v25
	v_add_lshl_u32 v112, v26, v21, 1
	v_or_b32_e32 v26, 0x100, v179
	v_lshrrev_b32_e32 v26, 3, v26
	s_cselect_b32 s0, s23, 3
	v_mul_u32_u24_e32 v27, 0x910, v26
	s_cmp_gt_u32 s0, 1
	v_add_lshl_u32 v114, v27, v21, 1
	v_or_b32_e32 v27, 0xc0, v179
	s_cselect_b64 s[38:39], -1, 0
	v_lshrrev_b32_e32 v27, 3, v27
	v_writelane_b32 v254, s38, 23
	v_mul_u32_u24_e32 v28, 0x910, v27
	s_movk_i32 s1, 0x1d1
	v_writelane_b32 v254, s39, 24
	v_add_lshl_u32 v116, v28, v21, 1
	v_or_b32_e32 v28, 0x80, v179
	s_ashr_i32 s76, s22, 8
	v_cmp_gt_u32_e64 s[22:23], s1, v22
	v_lshrrev_b32_e32 v28, 3, v28
	s_cmp_lt_u32 s26, 2
	v_writelane_b32 v254, s22, 51
	v_mul_u32_u24_e32 v29, 0x910, v28
	v_add_lshl_u32 v118, v29, v21, 1
	v_writelane_b32 v254, s23, 52
	s_cselect_b64 s[22:23], -1, 0
	s_cmp_gt_u32 s26, 1
	v_or_b32_e32 v29, 64, v179
	s_cselect_b64 s[26:27], -1, 0
	s_cmp_gt_u32 s0, 2
	v_lshrrev_b32_e32 v29, 3, v29
	s_cselect_b64 s[0:1], -1, 0
	v_mul_u32_u24_e32 v30, 0x910, v29
	v_writelane_b32 v254, s0, 62
	v_add_lshl_u32 v120, v30, v21, 1
	v_bfe_u32 v30, v1, 3, 3
	v_and_b32_e32 v1, 48, v1
	v_writelane_b32 v254, s1, 63
	s_movk_i32 s0, 0x1220
	v_mad_u32_u24 v126, v3, s0, v1
	v_mov_b32_e32 v127, v169
	s_mov_b64 s[0:1], 0x12200
	v_lshl_add_u64 v[128:129], v[126:127], 0, s[0:1]
	s_mov_b64 s[0:1], 0x24400
	v_lshl_add_u64 v[130:131], v[126:127], 0, s[0:1]
	s_mov_b64 s[0:1], 0x36600
	v_readlane_b32 s74, v254, 21
	v_lshlrev_b32_e32 v168, 2, v179
	v_lshl_add_u64 v[132:133], v[126:127], 0, s[0:1]
	v_readlane_b32 s75, v254, 22
	s_add_u32 s0, s78, s74
	v_add_u32_e32 v206, s40, v168
	v_lshl_add_u64 v[124:125], s[2:3], 0, v[168:169]
	v_add_u32_e32 v168, 0x200, v126
	s_addc_u32 s1, s79, s75
	v_lshl_add_u64 v[134:135], s[0:1], 0, v[168:169]
	v_add_u32_e32 v168, 0x12400, v126
	v_lshl_add_u64 v[136:137], s[0:1], 0, v[168:169]
	v_add_u32_e32 v168, 0x24600, v126
	s_lshl_b32 s2, s76, 6
	v_lshl_add_u64 v[138:139], s[0:1], 0, v[168:169]
	v_add_u32_e32 v168, 0x36800, v126
	v_writelane_b32 v255, s2, 0
	v_lshl_add_u64 v[140:141], s[0:1], 0, v[168:169]
	s_movk_i32 s2, 0x910
	v_readlane_b32 s0, v253, 48
	v_mad_u32_u24 v1, v30, s2, v20
	s_add_u32 s0, s0, s74
	v_readlane_b32 s1, v253, 49
	v_lshl_add_u32 v168, v1, 1, v171
	s_addc_u32 s1, s1, s75
	v_mad_u32_u24 v1, v29, s2, v20
	v_lshl_add_u64 v[142:143], s[0:1], 0, v[168:169]
	v_lshl_add_u32 v168, v1, 1, v171
	v_mad_u32_u24 v1, v28, s2, v20
	v_lshl_add_u64 v[144:145], s[0:1], 0, v[168:169]
	v_lshl_add_u32 v168, v1, 1, v171
	v_mad_u32_u24 v1, v27, s2, v20
	v_lshl_add_u64 v[146:147], s[0:1], 0, v[168:169]
	v_lshl_add_u32 v168, v1, 1, v171
	v_mad_u32_u24 v1, v26, s2, v20
	v_lshl_add_u64 v[148:149], s[0:1], 0, v[168:169]
	v_lshl_add_u32 v168, v1, 1, v171
	v_mad_u32_u24 v1, v25, s2, v20
	v_lshl_add_u64 v[150:151], s[0:1], 0, v[168:169]
	v_lshl_add_u32 v168, v1, 1, v171
	v_mad_u32_u24 v1, v24, s2, v20
	v_lshl_add_u64 v[152:153], s[0:1], 0, v[168:169]
	v_lshl_add_u32 v168, v1, 1, v171
	v_mad_u32_u24 v1, v23, s2, v20
	v_mul_u32_u24_e32 v31, 0x910, v30
	v_lshlrev_b32_e32 v2, 3, v2
	v_lshl_add_u64 v[154:155], s[0:1], 0, v[168:169]
	v_lshl_add_u32 v168, v1, 1, v171
	v_mov_b32_e32 v84, 0
	v_add_lshl_u32 v122, v21, v31, 1
	v_mov_b32_e32 v123, v169
	v_mov_b32_e32 v121, v169
	v_mov_b32_e32 v119, v169
	v_mov_b32_e32 v117, v169
	v_mov_b32_e32 v115, v169
	v_mov_b32_e32 v113, v169
	v_mov_b32_e32 v111, v169
	v_mov_b32_e32 v109, v169
	v_cmp_lt_i32_e64 s[42:43], -1, v6
	v_cmp_lt_i32_e64 s[44:45], -1, v7
	v_cmp_lt_i32_e64 s[46:47], -1, v8
	v_cmp_lt_i32_e64 s[48:49], -1, v9
	v_cmp_lt_i32_e64 s[50:51], -1, v10
	v_cmp_lt_i32_e64 s[52:53], -1, v11
	v_cmp_lt_i32_e64 s[54:55], -1, v12
	v_cmp_lt_i32_e64 s[56:57], -1, v13
	v_cmp_lt_i32_e64 s[58:59], -1, v14
	v_cmp_lt_i32_e64 s[60:61], -1, v15
	v_cmp_lt_i32_e64 s[62:63], -1, v16
	v_cmp_lt_i32_e64 s[64:65], -1, v4
	v_cmp_lt_i32_e64 s[66:67], -1, v17
	v_cmp_lt_i32_e64 s[68:69], -1, v18
	v_cmp_lt_i32_e64 s[70:71], -1, v19
	v_cmp_lt_i32_e64 s[72:73], -1, v5
	s_mov_b32 s41, s34
	v_writelane_b32 v254, s76, 31
	v_lshl_add_u64 v[156:157], s[0:1], 0, v[168:169]
	v_lshlrev_b32_e32 v207, 2, v6
	v_lshlrev_b32_e32 v208, 2, v7
	v_lshlrev_b32_e32 v209, 2, v8
	v_lshlrev_b32_e32 v210, 2, v9
	v_lshlrev_b32_e32 v211, 2, v10
	v_lshlrev_b32_e32 v212, 2, v11
	v_lshlrev_b32_e32 v213, 2, v12
	v_lshlrev_b32_e32 v214, 2, v13
	v_lshlrev_b32_e32 v215, 2, v14
	v_lshlrev_b32_e32 v216, 2, v15
	v_lshlrev_b32_e32 v217, 2, v16
	v_lshlrev_b32_e32 v218, 2, v4
	v_lshlrev_b32_e32 v219, 2, v17
	v_lshlrev_b32_e32 v220, 2, v18
	v_lshlrev_b32_e32 v221, 2, v19
	v_lshlrev_b32_e32 v222, 2, v5
	v_mov_b32_e32 v170, 0x7c
	v_cndmask_b32_e64 v207, v170, v207, s[42:43]
	v_cndmask_b32_e64 v208, v170, v208, s[44:45]
	v_cndmask_b32_e64 v209, v170, v209, s[46:47]
	v_cndmask_b32_e64 v210, v170, v210, s[48:49]
	v_cndmask_b32_e64 v211, v170, v211, s[50:51]
	v_cndmask_b32_e64 v212, v170, v212, s[52:53]
	v_cndmask_b32_e64 v213, v170, v213, s[54:55]
	v_cndmask_b32_e64 v214, v170, v214, s[56:57]
	v_cndmask_b32_e64 v215, v170, v215, s[58:59]
	v_cndmask_b32_e64 v216, v170, v216, s[60:61]
	v_cndmask_b32_e64 v217, v170, v217, s[62:63]
	v_cndmask_b32_e64 v218, v170, v218, s[64:65]
	v_cndmask_b32_e64 v219, v170, v219, s[66:67]
	v_cndmask_b32_e64 v220, v170, v220, s[68:69]
	v_cndmask_b32_e64 v221, v170, v221, s[70:71]
	v_cndmask_b32_e64 v222, v170, v222, s[72:73]
	v_lshlrev_b32_e32 v168, 1, v2
	v_lshlrev_b32_e32 v158, 1, v0
	v_mov_b32_e32 v85, v84
	v_mov_b32_e32 v86, v84
	v_mov_b32_e32 v87, v84
	v_mov_b32_e32 v80, v84
	v_mov_b32_e32 v81, v84
	v_mov_b32_e32 v82, v84
	v_mov_b32_e32 v83, v84
	v_mov_b32_e32 v76, v84
	v_mov_b32_e32 v77, v84
	v_mov_b32_e32 v78, v84
	v_mov_b32_e32 v79, v84
	v_mov_b32_e32 v64, v84
	v_mov_b32_e32 v65, v84
	v_mov_b32_e32 v66, v84
	v_mov_b32_e32 v67, v84
	s_branch .LBB0_694

.LBB0_694:
	s_lshr_b32 s0, s34, 6
	s_and_b32 s0, s0, 2
	v_readlane_b32 s1, v254, 31
	s_add_i32 s0, s0, s1
	s_mul_i32 s2, s0, 0x1d1
	s_ashr_i32 s3, s2, 31
	v_lshl_add_u64 v[68:69], s[2:3], 2, v[124:125]
	global_load_dword v70, v[68:69], off
	global_load_dword v71, v[68:69], off offset:256
	global_load_dword v72, v[68:69], off offset:512
	global_load_dword v73, v[68:69], off offset:768
	global_load_dword v74, v[68:69], off offset:1024
	global_load_dword v75, v[68:69], off offset:1280
	global_load_dword v76, v[68:69], off offset:1536
	s_mov_b64 s[2:3], exec
	v_readlane_b32 s20, v254, 51
	v_readlane_b32 s21, v254, 52
	s_and_b64 s[20:21], s[2:3], s[20:21]
	s_movk_i32 s74, 0x1220
	s_mov_b64 exec, s[20:21]
	global_load_dword v77, v[68:69], off offset:1792
	s_mov_b64 exec, s[2:3]
	s_waitcnt vmcnt(0)
	v_mul_f32_e32 v70, 0x3fb8aa3b, v70
	v_mul_f32_e32 v71, 0x3fb8aa3b, v71
	v_mul_f32_e32 v72, 0x3fb8aa3b, v72
	v_mul_f32_e32 v73, 0x3fb8aa3b, v73
	v_mul_f32_e32 v74, 0x3fb8aa3b, v74
	v_mul_f32_e32 v75, 0x3fb8aa3b, v75
	v_mul_f32_e32 v76, 0x3fb8aa3b, v76
	v_mov_b32_e32 v88, v224
	v_mul_u32_u24_e32 v88, 0x843, v88
	v_lshrrev_b32_e32 v88, 16, v88
	v_lshl_add_u32 v88, v88, 2, v206
	v_add_u32_e32 v89, 64, v224
	v_mul_u32_u24_e32 v89, 0x843, v89
	v_lshrrev_b32_e32 v89, 16, v89
	v_lshl_add_u32 v89, v89, 2, v206
	v_add_u32_e32 v90, 0x80, v224
	v_mul_u32_u24_e32 v90, 0x843, v90
	v_lshrrev_b32_e32 v90, 16, v90
	v_lshl_add_u32 v90, v90, 2, v206
	v_add_u32_e32 v91, 0xc0, v224
	v_mul_u32_u24_e32 v91, 0x843, v91
	v_lshrrev_b32_e32 v91, 16, v91
	v_lshl_add_u32 v91, v91, 2, v206
	v_add_u32_e32 v92, 0x100, v224
	v_mul_u32_u24_e32 v92, 0x843, v92
	v_lshrrev_b32_e32 v92, 16, v92
	v_lshl_add_u32 v92, v92, 2, v206
	v_add_u32_e32 v93, 0x140, v224
	v_mul_u32_u24_e32 v93, 0x843, v93
	v_lshrrev_b32_e32 v93, 16, v93
	v_lshl_add_u32 v93, v93, 2, v206
	v_add_u32_e32 v94, 0x180, v224
	v_mul_u32_u24_e32 v94, 0x843, v94
	v_lshrrev_b32_e32 v94, 16, v94
	v_lshl_add_u32 v94, v94, 2, v206
	v_add_u32_e32 v95, 0x1c0, v224
	v_mul_u32_u24_e32 v95, 0x843, v95
	v_lshrrev_b32_e32 v95, 16, v95
	v_lshl_add_u32 v95, v95, 2, v206
	ds_write_b32 v88, v70 offset:8384
	ds_write_b32 v89, v71 offset:8640
	ds_write_b32 v90, v72 offset:8896
	ds_write_b32 v91, v73 offset:9152
	ds_write_b32 v92, v74 offset:9408
	ds_write_b32 v93, v75 offset:9664
	ds_write_b32 v94, v76 offset:9920
	v_lshlrev_b32_e32 v96, 7, v224
	v_add_u32_e32 v96, s40, v96
	v_mov_b32_e32 v97, 0xf149f2ca
	v_cmp_gt_u32_e32 vcc, 15, v224
	s_and_b64 exec, s[2:3], vcc
	ds_write_b32 v96, v97 offset:8508
	s_mov_b64 exec, s[20:21]
	v_mul_f32_e32 v77, 0x3fb8aa3b, v77
	ds_write_b32 v95, v77 offset:10176

.LBB0_712:
	s_and_b32 s3, s41, 0x7f
	v_sub_u32_e64 v90, s3, 4 clamp
	s_movk_i32 s0, 0x78
	v_cmp_gt_u32_e32 vcc, s0, v90
	v_mov_b32_e32 v88, 0x78
	s_mov_b32 s0, 0x48800
	v_cndmask_b32_e32 v88, v88, v90, vcc
	v_mul_hi_u32 v89, v88, s0
	v_mul_lo_u32 v88, v88, s0
	s_and_b32 s0, s34, 0x80
	v_readlane_b32 s1, v255, 0
	s_add_i32 s0, s1, s0
	s_ashr_i32 s1, s0, 31
	s_lshl_b64 s[38:39], s[0:1], 1
	v_readfirstlane_b32 s0, v90
	s_min_u32 s0, s0, 0x78
	s_mulk_i32 s0, 0x80
	s_mulk_i32 s3, 0x80
	s_sub_i32 s0, s0, s3
	s_mul_hi_i32 s3, s2, 0x2440000
	s_mul_i32 s2, s2, 0x2440000
	v_lshl_add_u64 v[88:89], s[2:3], 0, v[88:89]
	v_lshl_add_u64 v[88:89], v[88:89], 0, s[38:39]
	v_mov_b32_e32 v159, 0
	s_add_i32 s0, s40, s0
	v_lshl_add_u64 v[162:163], v[134:135], 0, v[88:89]
	v_lshl_add_u64 v[164:165], v[136:137], 0, v[88:89]
	v_lshl_add_u64 v[166:167], v[138:139], 0, v[88:89]
	v_lshl_add_u64 v[186:187], v[140:141], 0, v[88:89]
	v_lshl_add_u64 v[188:189], v[142:143], 0, v[88:89]
	v_lshl_add_u64 v[190:191], v[144:145], 0, v[88:89]
	v_lshl_add_u64 v[192:193], v[146:147], 0, v[88:89]
	v_lshl_add_u64 v[194:195], v[148:149], 0, v[88:89]
	v_lshl_add_u64 v[196:197], v[150:151], 0, v[88:89]
	v_lshl_add_u64 v[198:199], v[152:153], 0, v[88:89]
	v_lshl_add_u64 v[200:201], v[154:155], 0, v[88:89]
	v_lshl_add_u64 v[202:203], v[156:157], 0, v[88:89]
	v_mov_b32_e32 v106, 0xf149f2ca
	s_mov_b64 s[2:3], 0
	v_mov_b32_e32 v100, 0
	v_mov_b32_e32 v101, v159
	v_mov_b32_e32 v102, v159
	v_mov_b32_e32 v103, v159
	v_mov_b32_e32 v96, 0
	v_mov_b32_e32 v97, v159
	v_mov_b32_e32 v98, v159
	v_mov_b32_e32 v99, v159
	v_mov_b32_e32 v92, 0
	v_mov_b32_e32 v93, v159
	v_mov_b32_e32 v94, v159
	v_mov_b32_e32 v95, v159
	v_mov_b32_e32 v88, 0
	v_mov_b32_e32 v89, v159
	v_mov_b32_e32 v90, v159
	v_mov_b32_e32 v91, v159
	s_mov_b32 s1, 0xf149f2ca

.LBB0_752:
	v_mov_b32_e32 v243, 0xf149f2ca
	s_andn2_b64 vcc, exec, s[38:39]
	v_mov_b32_e32 v244, 0xf149f2ca
	v_mov_b32_e32 v107, 0xf149f2ca
	v_mov_b32_e32 v204, 0xf149f2ca
	v_mov_b32_e32 v104, 0xf149f2ca
	s_cbranch_vccnz .LBB0_762
	v_add_u32_e32 v245, s0, v207
	v_add_u32_e32 v246, s0, v208
	v_add_u32_e32 v247, s0, v209
	v_add_u32_e32 v248, s0, v210
	ds_read_b32 v204, v245 offset:9280
	ds_read_b32 v107, v246 offset:9280
	ds_read_b32 v244, v247 offset:9280
	ds_read_b32 v243, v248 offset:9280
	s_waitcnt lgkmcnt(0)
	v_fmac_f32_e32 v204, 0x3e38aa3b, v84
	v_fmac_f32_e32 v107, 0x3e38aa3b, v85
	v_fmac_f32_e32 v244, 0x3e38aa3b, v86
	v_fmac_f32_e32 v243, 0x3e38aa3b, v87
	v_max3_f32 v84, v204, s1, v107
	v_max3_f32 v104, v84, v244, v243
.LBB0_762:
	s_and_b64 vcc, exec, s[74:75]
	s_mov_b64 s[38:39], -1
	s_cbranch_vccnz .LBB0_772
	v_add_u32_e32 v249, s0, v211
	v_add_u32_e32 v250, s0, v212
	v_add_u32_e32 v251, s0, v213
	v_add_u32_e32 v235, s0, v214
	ds_read_b32 v246, v249 offset:9280
	ds_read_b32 v245, v250 offset:9280
	ds_read_b32 v248, v251 offset:9280
	ds_read_b32 v247, v235 offset:9280
	s_waitcnt lgkmcnt(0)
	v_fmac_f32_e32 v246, 0x3e38aa3b, v80
	v_fmac_f32_e32 v245, 0x3e38aa3b, v81
	v_fmac_f32_e32 v248, 0x3e38aa3b, v82
	v_fmac_f32_e32 v247, 0x3e38aa3b, v83
	v_max3_f32 v80, v104, v246, v245
	v_max3_f32 v84, v80, v248, v247
	s_branch .LBB0_774

.LBB0_774:
	s_and_b64 vcc, exec, s[76:77]
	s_mov_b64 s[38:39], -1
	s_cbranch_vccnz .LBB0_784
	v_add_u32_e32 v237, s0, v215
	v_add_u32_e32 v236, s0, v216
	v_add_u32_e32 v233, s0, v217
	v_add_u32_e32 v225, s0, v218
	ds_read_b32 v250, v237 offset:9280
	ds_read_b32 v249, v236 offset:9280
	ds_read_b32 v235, v233 offset:9280
	ds_read_b32 v251, v225 offset:9280
	s_waitcnt lgkmcnt(0)
	v_fmac_f32_e32 v250, 0x3e38aa3b, v76
	v_fmac_f32_e32 v249, 0x3e38aa3b, v77
	v_fmac_f32_e32 v235, 0x3e38aa3b, v78
	v_fmac_f32_e32 v251, 0x3e38aa3b, v79
	v_max3_f32 v76, v84, v250, v249
	v_max3_f32 v80, v76, v235, v251
	s_branch .LBB0_786

.LBB0_786:
	s_and_b64 vcc, exec, s[78:79]
	s_mov_b64 s[38:39], -1
	s_cbranch_vccnz .LBB0_796
	v_add_u32_e32 v234, s0, v219
	v_add_u32_e32 v241, s0, v220
	v_add_u32_e32 v242, s0, v221
	v_add_u32_e32 v223, s0, v222
	ds_read_b32 v237, v234 offset:9280
	ds_read_b32 v236, v241 offset:9280
	ds_read_b32 v233, v242 offset:9280
	ds_read_b32 v225, v223 offset:9280
	s_waitcnt lgkmcnt(0)
	v_fmac_f32_e32 v237, 0x3e38aa3b, v64
	v_fmac_f32_e32 v236, 0x3e38aa3b, v65
	v_fmac_f32_e32 v233, 0x3e38aa3b, v66
	v_fmac_f32_e32 v225, 0x3e38aa3b, v67
	v_max3_f32 v64, v80, v237, v236
	v_max3_f32 v76, v64, v233, v225
	s_branch .LBB0_798

.LBB0_818:
	s_add_u32 s2, s2, 0x48800
	s_addc_u32 s3, s3, 0
	s_addk_i32 s0, 0x80
	s_cmp_eq_u32 s2, 0x244000
	s_cbranch_scc1 .LBB0_693
	v_mov_b32_e32 v106, v241
	s_branch .LBB0_713
